# G1 epilogue q/k loops: qk-norm weight pointer taken from v255 lanes filled once in the kernel prologue instead of a kernarg global load and wait per loop
# baseline (speedup 1.0000x reference)
.LBB0_5:
	s_or_b64 exec, exec, s[4:5]
	v_readlane_b32 s4, v253, 1
	v_readlane_b32 s5, v253, 2
	s_load_dwordx2 s[30:31], s[4:5], 0x110
	s_waitcnt lgkmcnt(0)
	s_cmp_ge_i32 s30, s31
	s_cbranch_scc1 .LBB0_833
	s_cmpk_gt_i32 s31, 0x1000
	v_lshrrev_b32_e32 v1, 20, v0
	v_lshrrev_b32_e32 v0, 10, v0
	s_cselect_b64 s[6:7], -1, 0
	v_or_b32_e32 v0, v0, v1
	s_movk_i32 s5, 0x3ff
	v_writelane_b32 v253, s6, 7
	v_and_or_b32 v0, v0, s5, v202
	s_mov_b64 s[16:17], s[64:65]
	v_writelane_b32 v253, s7, 8
	v_cmp_eq_u32_e64 s[6:7], 0, v0
	s_mul_i32 s4, s17, s16
	v_mbcnt_lo_u32_b32 v0, -1, 0
	v_writelane_b32 v253, s6, 9
	v_mbcnt_hi_u32_b32 v207, -1, v0
	v_and_b32_e32 v0, 64, v207
	v_writelane_b32 v253, s7, 10
	s_movk_i32 s75, 0x1000
	v_readlane_b32 s10, v253, 1
	v_readlane_b32 s11, v253, 2
	s_load_dword s5, s[10:11], 0x120
	s_mov_b32 s9, 0
	v_mov_b32_e32 v1, 0
	v_mov_b32_e32 v203, 0x22000
	v_mov_b32_e32 v204, 0x22004
	s_waitcnt lgkmcnt(0)
	s_mul_i32 s68, s4, s5
	s_add_u32 s4, s0, 0x16ab8200
	s_addc_u32 s5, s1, 0
	s_add_u32 s80, s0, 0x16ab8400
	v_writelane_b32 v253, s4, 11
	s_addc_u32 s81, s1, 0
	v_mov_b32_e32 v205, 0x358637bd
	v_writelane_b32 v253, s5, 12
	s_add_u32 s4, s0, 0x16ab8500
	s_addc_u32 s5, s1, 0
	v_writelane_b32 v253, s4, 13
	s_mov_b32 s33, 0x800000
	s_movk_i32 s82, 0x6000
	v_writelane_b32 v253, s5, 14
	s_add_u32 s4, s0, 0x16ab8600
	s_addc_u32 s5, s1, 0
	v_writelane_b32 v253, s4, 15
	s_mov_b64 s[96:97], 0xc0
	s_mov_b64 s[72:73], 0x100
	v_writelane_b32 v253, s5, 16
	s_add_u32 s4, s0, 0x16ab8700
	s_addc_u32 s5, s1, 0
	v_writelane_b32 v253, s4, 17
	s_movk_i32 s83, 0x110
	s_mov_b64 s[76:77], 0x4000
	v_writelane_b32 v253, s5, 18
	s_add_u32 s4, s0, 0x16ab8800
	s_addc_u32 s5, s1, 0
	v_writelane_b32 v253, s4, 19
	s_movk_i32 s84, 0xc00
	s_mov_b32 s74, 0x3fb8aa3b
	v_writelane_b32 v253, s5, 20
	s_add_u32 s4, s0, 0x16ab8900
	s_addc_u32 s5, s1, 0
	v_writelane_b32 v253, s4, 21
	v_mov_b32_e32 v206, 0x22010
	s_movk_i32 s85, 0xfefe
	v_writelane_b32 v253, s5, 22
	s_add_u32 s4, s0, 0x16ab8a00
	s_addc_u32 s5, s1, 0
	v_writelane_b32 v253, s4, 23
	v_add_u32_e32 v208, 64, v0
	v_xor_b32_e32 v209, 32, v207
	v_writelane_b32 v253, s5, 24
	s_add_u32 s4, s0, 0x16ab8b00
	s_addc_u32 s5, s1, 0
	v_writelane_b32 v253, s4, 25
	v_xor_b32_e32 v210, 16, v207
	v_xor_b32_e32 v211, 8, v207
	v_writelane_b32 v253, s5, 26
	s_add_u32 s4, s0, 0x16ab8c00
	s_addc_u32 s5, s1, 0
	v_writelane_b32 v253, s4, 27
	v_xor_b32_e32 v212, 4, v207
	v_xor_b32_e32 v213, 2, v207
	v_writelane_b32 v253, s5, 28
	s_add_u32 s4, s0, 0x16ab8d00
	s_addc_u32 s5, s1, 0
	v_writelane_b32 v253, s4, 29
	v_xor_b32_e32 v214, 1, v207
	v_mov_b32_e32 v215, 0xf149f2ca
	v_writelane_b32 v253, s5, 30
	s_add_u32 s4, s0, 0x16ab8e00
	s_addc_u32 s5, s1, 0
	v_writelane_b32 v253, s4, 31
	v_mov_b32_e32 v216, 0x1000000
	v_mov_b32_e32 v217, 0xa8
	v_writelane_b32 v253, s5, 32
	s_add_u32 s4, s0, 0x16ab8f00
	s_addc_u32 s5, s1, 0
	v_writelane_b32 v253, s4, 33
	v_mov_b32_e32 v218, 0xa0
	v_mov_b32_e32 v219, 0x80
	v_writelane_b32 v253, s5, 34
	s_add_u32 s4, s0, 0x16ab9000
	s_addc_u32 s5, s1, 0
	v_writelane_b32 v253, s4, 35
	v_mov_b32_e32 v220, 0x1c00000
	v_mov_b32_e32 v221, 0x1800000
	v_writelane_b32 v253, s5, 36
	s_add_u32 s4, s0, 0x16ab9100
	s_addc_u32 s5, s1, 0
	v_writelane_b32 v253, s4, 37
	v_mov_b32_e32 v222, 0x800000
	v_mov_b32_e32 v224, 0xfffff500
	v_writelane_b32 v253, s5, 38
	s_add_u32 s4, s0, 0x16ab9200
	s_addc_u32 s5, s1, 0
	v_writelane_b32 v253, s4, 39
	v_mov_b32_e32 v225, 0xc0
	v_mov_b32_e32 v252, 0x7fffe200
	v_writelane_b32 v253, s5, 40
	s_add_u32 s4, s0, 0x16ab9300
	s_addc_u32 s5, s1, 0
	v_writelane_b32 v253, s4, 41
	s_cmp_eq_u32 s8, 15
	v_mov_b32_e32 v223, 0xc8
	v_writelane_b32 v253, s5, 42
	s_cselect_b64 s[4:5], -1, 0
	v_writelane_b32 v253, s4, 43
	s_cmp_eq_u32 s8, 14
	v_mov_b32_e32 v228, 0xb8
	v_writelane_b32 v253, s5, 44
	s_cselect_b64 s[4:5], -1, 0
	v_writelane_b32 v253, s4, 45
	s_cmp_eq_u32 s8, 13
	v_mov_b32_e32 v229, 0xfffd0000
	v_writelane_b32 v253, s5, 46
	s_cselect_b64 s[4:5], -1, 0
	v_writelane_b32 v253, s4, 47
	s_cmp_eq_u32 s8, 12
	s_nop 0
	v_writelane_b32 v253, s5, 48
	s_cselect_b64 s[4:5], -1, 0
	v_writelane_b32 v253, s4, 49
	s_cmp_eq_u32 s8, 11
	s_nop 0
	v_writelane_b32 v253, s5, 50
	s_cselect_b64 s[4:5], -1, 0
	v_writelane_b32 v253, s4, 51
	s_cmp_eq_u32 s8, 10
	s_nop 0
	v_writelane_b32 v253, s5, 52
	s_cselect_b64 s[4:5], -1, 0
	v_writelane_b32 v253, s4, 53
	s_cmp_eq_u32 s8, 9
	s_nop 0
	v_writelane_b32 v253, s5, 54
	s_cselect_b64 s[4:5], -1, 0
	v_writelane_b32 v253, s4, 55
	s_cmp_eq_u32 s8, 8
	s_nop 0
	v_writelane_b32 v253, s5, 56
	s_cselect_b64 s[4:5], -1, 0
	v_writelane_b32 v253, s4, 57
	s_cmp_eq_u32 s8, 7
	s_nop 0
	v_writelane_b32 v253, s5, 58
	s_cselect_b64 s[4:5], -1, 0
	v_writelane_b32 v253, s4, 59
	s_cmp_eq_u32 s8, 6
	s_nop 0
	v_writelane_b32 v253, s5, 60
	s_cselect_b64 s[4:5], -1, 0
	v_writelane_b32 v253, s4, 61
	s_cmp_eq_u32 s8, 5
	s_nop 0
	v_writelane_b32 v253, s5, 62
	s_cselect_b64 s[4:5], -1, 0
	v_writelane_b32 v253, s4, 63
	s_cmp_eq_u32 s8, 4
	s_nop 0
	v_writelane_b32 v254, s5, 0
	s_cselect_b64 s[4:5], -1, 0
	v_writelane_b32 v254, s4, 1
	s_cmp_eq_u32 s8, 3
	s_nop 0
	v_writelane_b32 v254, s5, 2
	s_cselect_b64 s[4:5], -1, 0
	v_writelane_b32 v254, s4, 3
	s_cmp_eq_u32 s8, 2
	s_nop 0
	v_writelane_b32 v254, s5, 4
	s_cselect_b64 s[4:5], -1, 0
	v_writelane_b32 v254, s4, 5
	s_cmp_eq_u32 s8, 1
	s_nop 0
	v_writelane_b32 v254, s5, 6
	s_cselect_b64 s[4:5], -1, 0
	v_writelane_b32 v254, s4, 7
	s_cmp_eq_u32 s8, 0
	s_nop 0
	v_writelane_b32 v254, s5, 8
	s_cselect_b64 s[4:5], -1, 0
	v_writelane_b32 v254, s4, 9
	s_nop 1
	v_writelane_b32 v254, s5, 10
	s_lshl_b32 s4, s8, 8
	s_add_u32 s2, s2, s4
	s_addc_u32 s3, s3, 0
	s_add_u32 s4, s2, 0x1400
	s_addc_u32 s5, s3, 0
	v_writelane_b32 v254, s4, 11
	s_add_u32 s2, s2, 0x2400
	s_addc_u32 s3, s3, 0
	v_writelane_b32 v254, s5, 12
	v_writelane_b32 v254, s2, 13
	v_readlane_b32 s8, v253, 0
	s_nop 0
	v_writelane_b32 v254, s3, 14
	s_add_u32 s2, s0, 0x16abb400
	s_addc_u32 s3, s1, 0
	v_writelane_b32 v254, s2, 15
	s_add_u32 s0, s0, 0x16abb500
	s_addc_u32 s1, s1, 0
	v_writelane_b32 v254, s3, 16
	v_writelane_b32 v254, s0, 17
	s_lshl_b32 s70, s16, 3
	s_nop 0
	v_writelane_b32 v254, s1, 18
	s_lshl_b32 s0, s8, 3
	v_writelane_b32 v254, s0, 19
	s_load_dwordx4 s[12:15], s[10:11], 0xf0
	s_load_dwordx8 s[0:7], s[10:11], 0xd0
	s_load_dwordx16 s[48:63], s[10:11], 0x40
	s_waitcnt lgkmcnt(0)
	s_add_u32 s66, s14, 0x86b8000
	v_writelane_b32 v254, s0, 20
	s_addc_u32 s67, s15, 0
	s_cmpk_lt_i32 s8, 0xfd0
	v_writelane_b32 v254, s1, 21
	v_writelane_b32 v254, s2, 22
	v_writelane_b32 v254, s3, 23
	v_writelane_b32 v254, s4, 24
	v_writelane_b32 v254, s5, 25
	v_writelane_b32 v254, s6, 26
	v_writelane_b32 v254, s7, 27
	s_cselect_b64 s[0:1], -1, 0
	v_writelane_b32 v254, s0, 28
	s_nop 1
	v_writelane_b32 v254, s1, 29
	s_add_u32 s0, s14, 0x116b8000
	s_addc_u32 s1, s15, 0
	v_writelane_b32 v254, s0, 30
	s_add_u32 s78, s14, 0x8678000
	s_addc_u32 s79, s15, 0
	v_writelane_b32 v254, s1, 31
	s_load_dwordx8 s[0:7], s[10:11], 0x0
	s_waitcnt lgkmcnt(0)
	v_writelane_b32 v254, s0, 32
	s_nop 1
	v_writelane_b32 v254, s1, 33
	v_writelane_b32 v254, s2, 34
	v_writelane_b32 v254, s3, 35
	v_writelane_b32 v254, s4, 36
	v_writelane_b32 v254, s5, 37
	v_writelane_b32 v254, s6, 38
	v_writelane_b32 v254, s7, 39
	s_add_u32 s6, s14, 0x8698000
	s_addc_u32 s7, s15, 0
	s_add_u32 s86, s14, 0x8600000
	s_addc_u32 s87, s15, 0
	s_add_u32 s46, s14, 0xceb8000
	s_addc_u32 s47, s15, 0
	s_cmpk_lg_i32 s16, 0x100
	s_cselect_b64 s[0:1], -1, 0
	v_writelane_b32 v254, s0, 40
	s_cmpk_lt_i32 s8, 0x100
	s_nop 0
	v_writelane_b32 v254, s1, 41
	s_cselect_b64 s[0:1], -1, 0
	v_writelane_b32 v254, s0, 42
	s_cmpk_lt_u32 s8, 0x100
	s_nop 0
	v_writelane_b32 v254, s1, 43
	s_cselect_b64 s[0:1], -1, 0
	v_writelane_b32 v254, s0, 44
	s_bfe_u32 s2, s8, 0x20003
	s_lshr_b32 s5, s8, 3
	v_writelane_b32 v254, s1, 45
	s_lshl_b32 s0, s8, 2
	s_and_b32 s1, s0, 28
	s_or_b32 s1, s2, s1
	s_lshl_b32 s1, s1, 8
	v_writelane_b32 v254, s1, 46
	s_and_b32 s0, s0, 0x380
	v_writelane_b32 v254, s0, 47
	s_addk_i32 s0, 0xff00
	v_writelane_b32 v254, s0, 48
	s_add_u32 s0, s14, 0xa6b8000
	s_addc_u32 s1, s15, 0
	v_writelane_b32 v254, s0, 49
	s_cmpk_lt_i32 s8, 0x2c0
	s_nop 0
	v_writelane_b32 v254, s1, 50
	s_cselect_b64 s[0:1], -1, 0
	v_writelane_b32 v254, s0, 51
	s_cmpk_lt_u32 s8, 0x2c0
	s_nop 0
	v_writelane_b32 v254, s1, 52
	s_cselect_b64 s[0:1], -1, 0
	v_writelane_b32 v254, s0, 53
	s_nop 1
	v_writelane_b32 v254, s1, 54
	s_add_u32 s0, s14, 0xfeb8000
	s_addc_u32 s1, s15, 0
	v_writelane_b32 v254, s0, 55
	s_nop 1
	v_writelane_b32 v254, s1, 56
	s_add_u32 s0, s14, 0xb6b8000
	s_addc_u32 s1, s15, 0
	v_writelane_b32 v254, s0, 57
	s_nop 1
	v_writelane_b32 v254, s1, 58
	s_add_u32 s0, s14, 0x16abb800
	v_writelane_b32 v254, s0, 59
	s_addc_u32 s0, s15, 0
	s_cmpk_gt_u32 s8, 0x7f
	v_writelane_b32 v254, s0, 60
	s_cselect_b64 s[0:1], -1, 0
	s_cmpk_eq_i32 s16, 0x100
	s_load_dwordx8 s[16:23], s[10:11], 0x80
	v_writelane_b32 v254, s0, 61
	s_mov_b64 s[10:11], 0x80
	s_nop 0
	v_writelane_b32 v254, s1, 62
	s_waitcnt lgkmcnt(0)
	v_writelane_b32 v254, s16, 63
	s_cselect_b64 s[0:1], -1, 0
	s_nop 0
	v_writelane_b32 v255, s17, 0
	v_writelane_b32 v255, s18, 1
	v_writelane_b32 v255, s19, 2
	v_writelane_b32 v255, s20, 3
	v_writelane_b32 v255, s21, 4
	v_writelane_b32 v255, s22, 5
	v_writelane_b32 v255, s23, 6
	v_writelane_b32 v255, s0, 7
	s_mov_b32 s16, s30
	s_nop 0
	v_writelane_b32 v255, s1, 8
	s_and_b64 s[0:1], s[0:1], exec
	s_cselect_b32 s0, 0x200, 0
	v_writelane_b32 v255, s0, 9
	s_lshl_b32 s0, s8, 4
	s_and_b32 s1, s0, 0x70
	s_and_b32 s3, s5, 0x1ffffff8
	s_add_i32 s3, s3, s1
	s_bfe_u32 s4, s8, 0x30003
	s_or_b32 s3, s3, s4
	s_addk_i32 s3, 0x180
	v_writelane_b32 v255, s3, 10
	s_add_i32 s1, s1, s5
	v_writelane_b32 v255, s5, 11
	s_add_i32 s3, s1, 0xf0
	v_writelane_b32 v255, s3, 12
	s_lshl_b32 s3, s8, 1
	s_lshr_b32 s5, s8, 6
	s_and_b32 s3, s3, 2
	s_add_i32 s3, s3, s5
	s_and_b32 s0, s0, 0x60
	s_lshl_b32 s3, s3, 3
	s_add_i32 s3, s3, s0
	s_addk_i32 s1, 0x70
	s_or_b32 s0, s3, s4
	s_cmpk_lt_u32 s8, 0x80
	s_cselect_b32 s0, s0, s1
	v_writelane_b32 v255, s0, 13
	s_add_u32 s0, s14, 0x15eb8000
	s_addc_u32 s1, s15, 0
	v_writelane_b32 v255, s0, 14
	s_movk_i32 s5, 0x1600
	s_movk_i32 s4, 0xbf
	v_writelane_b32 v255, s1, 15
	s_add_u32 s0, s14, 0x164b8000
	v_writelane_b32 v255, s0, 16
	s_addc_u32 s0, s15, 0
	s_cmpk_lt_i32 s8, 0x300
	v_writelane_b32 v255, s0, 17
	s_cselect_b64 s[0:1], -1, 0
	v_writelane_b32 v255, s0, 18
	s_cmpk_lt_u32 s8, 0x300
	s_movk_i32 s3, 0x17f
	v_writelane_b32 v255, s1, 19
	s_cselect_b64 s[0:1], -1, 0
	v_writelane_b32 v255, s0, 20
	s_ashr_i32 s71, s70, 31
	s_nop 0
	v_writelane_b32 v255, s1, 21
	s_lshl_b64 s[0:1], s[70:71], 10
	v_writelane_b32 v255, s0, 22
	s_nop 1
	v_writelane_b32 v255, s1, 23
	s_lshl_b64 s[0:1], s[70:71], 11
	v_writelane_b32 v255, s0, 24
	s_nop 1
	v_writelane_b32 v255, s1, 25
	s_add_u32 s0, s52, 0x2a000
	s_addc_u32 s1, s53, 0
	v_writelane_b32 v255, s0, 26
	s_mov_b64 s[52:53], 0x2000
	s_nop 0
	v_writelane_b32 v255, s1, 27
	s_add_u32 s0, s14, 0xa6b840c
	s_addc_u32 s1, s15, 0
	v_writelane_b32 v255, s0, 28
	s_nop 1
	v_writelane_b32 v255, s1, 29
	s_and_b32 s0, s8, 7
	s_lshl_b32 s0, s0, 10
	s_lshl_b32 s1, s2, 8
	s_or_b32 s0, s0, s1
	v_writelane_b32 v255, s0, 30
	v_writelane_b32 v255, s30, 31
	s_movk_i32 s1, 0xfff
	s_movk_i32 s2, 0x3bf
	v_writelane_b32 v255, s31, 32
	v_writelane_b32 v255, s68, 33
	v_writelane_b32 v255, s80, 34
	s_mov_b32 s0, 0x3e000000
	s_nop 0
	v_writelane_b32 v255, s81, 35
	v_writelane_b32 v255, s12, 36
	s_nop 1
	v_writelane_b32 v255, s13, 37
	v_writelane_b32 v255, s14, 38
	v_writelane_b32 v255, s15, 39
	v_mbcnt_lo_u32_b32 v6, -1, 0
	v_mbcnt_hi_u32_b32 v6, -1, v6
	v_lshlrev_b32_e32 v7, 2, v6
	v_readlane_b32 s88, v254, 63
	v_readlane_b32 s89, v255, 0
	v_readlane_b32 s90, v255, 1
	v_readlane_b32 s91, v255, 2
	v_readlane_b32 s92, v255, 3
	v_readlane_b32 s93, v255, 4
	v_readlane_b32 s94, v253, 1
	v_readlane_b32 s95, v253, 2
	s_nop 4
	s_load_dwordx4 s[36:39], s[94:95], 0x100
	s_load_dwordx4 s[40:43], s[94:95], 0xa0
	global_load_dword v10, v7, s[62:63]
	global_load_dword v11, v7, s[88:89]
	global_load_dword v12, v7, s[90:91]
	global_load_dword v13, v7, s[92:93]
	global_load_dword v14, v7, s[62:63] offset:256
	global_load_dword v15, v7, s[88:89] offset:256
	global_load_dword v16, v7, s[90:91] offset:256
	global_load_dword v17, v7, s[92:93] offset:256
	global_load_dword v18, v7, s[62:63] offset:512
	global_load_dword v19, v7, s[88:89] offset:512
	global_load_dword v20, v7, s[90:91] offset:512
	global_load_dword v21, v7, s[92:93] offset:512
	global_load_dword v22, v7, s[62:63] offset:768
	global_load_dword v23, v7, s[88:89] offset:768
	global_load_dword v24, v7, s[90:91] offset:768
	global_load_dword v25, v7, s[92:93] offset:768
	s_waitcnt vmcnt(0) lgkmcnt(0)
	v_writelane_b32 v255, s40, 47
	v_writelane_b32 v255, s41, 48
	v_writelane_b32 v255, s42, 49
	v_writelane_b32 v255, s43, 50
	v_mul_f32_e32 v10, v10, v11
	v_mul_f32_e32 v12, v12, v13
	v_xor_b32_e32 v8, 0x80, v7
	ds_bpermute_b32 v9, v8, v10
	ds_bpermute_b32 v26, v8, v12
	s_waitcnt lgkmcnt(0)
	v_add_f32_e32 v10, v10, v9
	v_add_f32_e32 v12, v12, v26
	v_xor_b32_e32 v8, 0x40, v7
	ds_bpermute_b32 v9, v8, v10
	ds_bpermute_b32 v26, v8, v12
	s_waitcnt lgkmcnt(0)
	v_add_f32_e32 v10, v10, v9
	v_add_f32_e32 v12, v12, v26
	v_xor_b32_e32 v8, 0x20, v7
	ds_bpermute_b32 v9, v8, v10
	ds_bpermute_b32 v26, v8, v12
	s_waitcnt lgkmcnt(0)
	v_add_f32_e32 v10, v10, v9
	v_add_f32_e32 v12, v12, v26
	v_xor_b32_e32 v8, 0x10, v7
	ds_bpermute_b32 v9, v8, v10
	ds_bpermute_b32 v26, v8, v12
	s_waitcnt lgkmcnt(0)
	v_add_f32_e32 v10, v10, v9
	v_add_f32_e32 v12, v12, v26
	v_xor_b32_e32 v8, 0x8, v7
	ds_bpermute_b32 v9, v8, v10
	ds_bpermute_b32 v26, v8, v12
	s_waitcnt lgkmcnt(0)
	v_add_f32_e32 v10, v10, v9
	v_add_f32_e32 v12, v12, v26
	v_xor_b32_e32 v8, 0x4, v7
	ds_bpermute_b32 v9, v8, v10
	ds_bpermute_b32 v26, v8, v12
	s_waitcnt lgkmcnt(0)
	v_add_f32_e32 v10, v10, v9
	v_add_f32_e32 v12, v12, v26
	v_mul_f32_e32 v10, 0x3fb8aa3b, v10
	v_mul_f32_e32 v12, 0x3fb8aa3b, v12
	v_exp_f32_e32 v10, v10
	v_exp_f32_e32 v12, v12
	s_nop 1
	v_sub_f32_e32 v10, v10, v12
	v_add_f32_e32 v10, s36, v10
	s_nop 1
	v_readfirstlane_b32 s88, v10
	s_nop 1
	v_writelane_b32 v255, s88, 43
	v_mul_f32_e32 v14, v14, v15
	v_mul_f32_e32 v16, v16, v17
	v_xor_b32_e32 v8, 0x80, v7
	ds_bpermute_b32 v9, v8, v14
	ds_bpermute_b32 v26, v8, v16
	s_waitcnt lgkmcnt(0)
	v_add_f32_e32 v14, v14, v9
	v_add_f32_e32 v16, v16, v26
	v_xor_b32_e32 v8, 0x40, v7
	ds_bpermute_b32 v9, v8, v14
	ds_bpermute_b32 v26, v8, v16
	s_waitcnt lgkmcnt(0)
	v_add_f32_e32 v14, v14, v9
	v_add_f32_e32 v16, v16, v26
	v_xor_b32_e32 v8, 0x20, v7
	ds_bpermute_b32 v9, v8, v14
	ds_bpermute_b32 v26, v8, v16
	s_waitcnt lgkmcnt(0)
	v_add_f32_e32 v14, v14, v9
	v_add_f32_e32 v16, v16, v26
	v_xor_b32_e32 v8, 0x10, v7
	ds_bpermute_b32 v9, v8, v14
	ds_bpermute_b32 v26, v8, v16
	s_waitcnt lgkmcnt(0)
	v_add_f32_e32 v14, v14, v9
	v_add_f32_e32 v16, v16, v26
	v_xor_b32_e32 v8, 0x8, v7
	ds_bpermute_b32 v9, v8, v14
	ds_bpermute_b32 v26, v8, v16
	s_waitcnt lgkmcnt(0)
	v_add_f32_e32 v14, v14, v9
	v_add_f32_e32 v16, v16, v26
	v_xor_b32_e32 v8, 0x4, v7
	ds_bpermute_b32 v9, v8, v14
	ds_bpermute_b32 v26, v8, v16
	s_waitcnt lgkmcnt(0)
	v_add_f32_e32 v14, v14, v9
	v_add_f32_e32 v16, v16, v26
	v_mul_f32_e32 v14, 0x3fb8aa3b, v14
	v_mul_f32_e32 v16, 0x3fb8aa3b, v16
	v_exp_f32_e32 v14, v14
	v_exp_f32_e32 v16, v16
	s_nop 1
	v_sub_f32_e32 v14, v14, v16
	v_add_f32_e32 v14, s37, v14
	s_nop 1
	v_readfirstlane_b32 s88, v14
	s_nop 1
	v_writelane_b32 v255, s88, 44
	v_mul_f32_e32 v18, v18, v19
	v_mul_f32_e32 v20, v20, v21
	v_xor_b32_e32 v8, 0x80, v7
	ds_bpermute_b32 v9, v8, v18
	ds_bpermute_b32 v26, v8, v20
	s_waitcnt lgkmcnt(0)
	v_add_f32_e32 v18, v18, v9
	v_add_f32_e32 v20, v20, v26
	v_xor_b32_e32 v8, 0x40, v7
	ds_bpermute_b32 v9, v8, v18
	ds_bpermute_b32 v26, v8, v20
	s_waitcnt lgkmcnt(0)
	v_add_f32_e32 v18, v18, v9
	v_add_f32_e32 v20, v20, v26
	v_xor_b32_e32 v8, 0x20, v7
	ds_bpermute_b32 v9, v8, v18
	ds_bpermute_b32 v26, v8, v20
	s_waitcnt lgkmcnt(0)
	v_add_f32_e32 v18, v18, v9
	v_add_f32_e32 v20, v20, v26
	v_xor_b32_e32 v8, 0x10, v7
	ds_bpermute_b32 v9, v8, v18
	ds_bpermute_b32 v26, v8, v20
	s_waitcnt lgkmcnt(0)
	v_add_f32_e32 v18, v18, v9
	v_add_f32_e32 v20, v20, v26
	v_xor_b32_e32 v8, 0x8, v7
	ds_bpermute_b32 v9, v8, v18
	ds_bpermute_b32 v26, v8, v20
	s_waitcnt lgkmcnt(0)
	v_add_f32_e32 v18, v18, v9
	v_add_f32_e32 v20, v20, v26
	v_xor_b32_e32 v8, 0x4, v7
	ds_bpermute_b32 v9, v8, v18
	ds_bpermute_b32 v26, v8, v20
	s_waitcnt lgkmcnt(0)
	v_add_f32_e32 v18, v18, v9
	v_add_f32_e32 v20, v20, v26
	v_mul_f32_e32 v18, 0x3fb8aa3b, v18
	v_mul_f32_e32 v20, 0x3fb8aa3b, v20
	v_exp_f32_e32 v18, v18
	v_exp_f32_e32 v20, v20
	s_nop 1
	v_sub_f32_e32 v18, v18, v20
	v_add_f32_e32 v18, s38, v18
	s_nop 1
	v_readfirstlane_b32 s88, v18
	s_nop 1
	v_writelane_b32 v255, s88, 45
	v_mul_f32_e32 v22, v22, v23
	v_mul_f32_e32 v24, v24, v25
	v_xor_b32_e32 v8, 0x80, v7
	ds_bpermute_b32 v9, v8, v22
	ds_bpermute_b32 v26, v8, v24
	s_waitcnt lgkmcnt(0)
	v_add_f32_e32 v22, v22, v9
	v_add_f32_e32 v24, v24, v26
	v_xor_b32_e32 v8, 0x40, v7
	ds_bpermute_b32 v9, v8, v22
	ds_bpermute_b32 v26, v8, v24
	s_waitcnt lgkmcnt(0)
	v_add_f32_e32 v22, v22, v9
	v_add_f32_e32 v24, v24, v26
	v_xor_b32_e32 v8, 0x20, v7
	ds_bpermute_b32 v9, v8, v22
	ds_bpermute_b32 v26, v8, v24
	s_waitcnt lgkmcnt(0)
	v_add_f32_e32 v22, v22, v9
	v_add_f32_e32 v24, v24, v26
	v_xor_b32_e32 v8, 0x10, v7
	ds_bpermute_b32 v9, v8, v22
	ds_bpermute_b32 v26, v8, v24
	s_waitcnt lgkmcnt(0)
	v_add_f32_e32 v22, v22, v9
	v_add_f32_e32 v24, v24, v26
	v_xor_b32_e32 v8, 0x8, v7
	ds_bpermute_b32 v9, v8, v22
	ds_bpermute_b32 v26, v8, v24
	s_waitcnt lgkmcnt(0)
	v_add_f32_e32 v22, v22, v9
	v_add_f32_e32 v24, v24, v26
	v_xor_b32_e32 v8, 0x4, v7
	ds_bpermute_b32 v9, v8, v22
	ds_bpermute_b32 v26, v8, v24
	s_waitcnt lgkmcnt(0)
	v_add_f32_e32 v22, v22, v9
	v_add_f32_e32 v24, v24, v26
	v_mul_f32_e32 v22, 0x3fb8aa3b, v22
	v_mul_f32_e32 v24, 0x3fb8aa3b, v24
	v_exp_f32_e32 v22, v22
	v_exp_f32_e32 v24, v24
	s_nop 1
	v_sub_f32_e32 v22, v22, v24
	v_add_f32_e32 v22, s39, v22
	s_nop 1
	v_readfirstlane_b32 s88, v22
	s_nop 1
	v_writelane_b32 v255, s88, 46
	s_branch .LBB0_8

.LBB0_706:
	s_or_saveexec_b64 s[24:25], s[24:25]
	v_lshlrev_b32_e32 v0, 2, v196
	v_readlane_b32 s30, v255, 30
	v_lshrrev_b32_e32 v132, 3, v196
	v_and_b32_e32 v143, 28, v0
	v_and_b32_e32 v0, 7, v200
	v_add_u32_e32 v168, s30, v167
	v_mul_u32_u24_e32 v180, 0x110, v132
	v_lshlrev_b32_e32 v144, 2, v143
	v_or_b32_e32 v169, -8, v132
	v_lshlrev_b32_e32 v182, 4, v0
	v_lshlrev_b32_e32 v138, 3, v0
	v_add_u32_e32 v181, v168, v132
	s_xor_b64 exec, exec, s[24:25]
	s_cbranch_execz .LBB0_722
	s_cmp_lg_u64 s[26:27], 0
	s_cselect_b32 s32, 47, 49
	s_xor_b64 s[26:27], s[26:27], -1
	v_or_b32_e32 v152, 0x80000, v136
	s_nop 1
	v_readlane_b32 s30, v255, s32
	s_add_i32 s32, s32, 1
	s_nop 3
	v_readlane_b32 s31, v255, s32
	s_nop 1
	v_mov_b32_e32 v160, s30
	v_mov_b32_e32 v161, s31
	v_or_b32_e32 v0, 0xc0000, v150
	v_or_b32_e32 v183, -8, v132
	v_lshlrev_b64 v[132:133], 1, v[134:135]
	s_and_b64 s[30:31], s[28:29], exec
	v_cndmask_b32_e64 v150, v150, v0, s[22:23]
	v_cndmask_b32_e64 v136, v136, v152, s[22:23]
	v_mad_i64_i32 v[132:133], s[22:23], v181, s84, v[132:133]
	s_cselect_b32 s22, 0x80, 64
	v_lshl_add_u64 v[134:135], v[150:151], 1, s[92:93]
	v_cvt_f32_ubyte0_e32 v150, s22
	v_rcp_iflag_f32_e32 v150, v150
	v_cndmask_b32_e64 v153, v220, v221, s[20:21]
	v_cndmask_b32_e64 v0, v153, v222, s[28:29]
	v_sub_u32_e32 v154, 0, v130
	v_mul_f32_e32 v150, 0x4f7ffffe, v150
	v_cvt_u32_f32_e32 v153, v150
	s_cselect_b32 s34, 2, 1
	s_cselect_b32 s35, 7, 6
	v_lshlrev_b32_e32 v0, 2, v0
	s_sub_i32 s23, 0, s22
	v_max_i32_e32 v152, v130, v154
	v_lshl_add_u64 v[154:155], s[12:13], 0, v[0:1]
	v_mul_lo_u32 v0, s23, v153
	v_mul_hi_u32 v0, v153, v0
	v_add_u32_e32 v0, v153, v0
	v_lshl_add_u64 v[132:133], v[130:131], 1, v[132:133]
	v_mul_hi_u32 v0, v152, v0
	v_lshl_add_u64 v[150:151], s[14:15], 0, v[132:133]
	v_mul_lo_u32 v132, v0, s22
	v_sub_u32_e32 v132, v152, v132
	v_add_u32_e32 v133, 1, v0
	v_cmp_le_u32_e32 vcc, s22, v132
	v_readlane_b32 s28, v255, 14
	v_mov_b32_e32 v145, v1
	v_cndmask_b32_e32 v0, v0, v133, vcc
	v_subrev_u32_e32 v133, s22, v132
	v_cndmask_b32_e32 v132, v132, v133, vcc
	v_add_u32_e32 v133, 1, v0
	v_cmp_le_u32_e32 vcc, s22, v132
	v_readlane_b32 s29, v255, 15
	v_add3_u32 v184, v166, v180, v182
	v_cndmask_b32_e32 v0, v0, v133, vcc
	v_xor_b32_e32 v0, v0, v131
	v_sub_u32_e32 v152, v0, v131
	v_mul_lo_u32 v0, v152, s22
	v_sub_u32_e32 v130, v130, v0
	v_ashrrev_i32_e32 v131, 31, v130
	v_lshlrev_b64 v[132:133], 1, v[130:131]
	v_lshl_add_u64 v[130:131], v[130:131], 2, v[154:155]
	v_lshl_add_u64 v[136:137], v[136:137], 1, s[28:29]
	v_lshl_add_u64 v[158:159], v[130:131], 0, v[144:145]
	v_mov_b32_e32 v139, v1
	v_lshlrev_b32_e32 v185, 5, v181
	v_lshl_add_u64 v[146:147], s[78:79], 0, v[144:145]
	v_lshl_add_u64 v[148:149], s[6:7], 0, v[144:145]
	v_ashrrev_i32_e32 v153, 31, v152
	v_lshl_add_u64 v[154:155], v[134:135], 0, v[132:133]
	v_lshl_add_u64 v[156:157], v[136:137], 0, v[132:133]
	s_mov_b64 s[22:23], 0
	s_waitcnt vmcnt(0)
	v_lshl_add_u64 v[130:131], s[90:91], 2, v[160:161]
	v_lshl_add_u64 v[160:161], v[130:131], 0, v[144:145]
	global_load_dwordx4 v[232:235], v[160:161], off
	global_load_dwordx4 v[236:239], v[160:161], off offset:128
	v_and_b32_e32 v0, 0x7fe0, v185
	v_lshlrev_b32_e32 v0, 2, v0
	v_lshl_add_u64 v[250:251], v[146:147], 0, v[0:1]
	global_load_dwordx4 v[242:245], v[250:251], off
	v_lshl_add_u64 v[250:251], v[148:149], 0, v[0:1]
	global_load_dwordx4 v[246:249], v[250:251], off
	global_load_dword v227, v[250:251], off
	global_load_dword v227, v[250:251], off
	s_branch .LBB0_709

.LBB0_765:
	s_andn2_saveexec_b64 s[22:23], s[22:23]
	s_cbranch_execz .LBB0_781
	s_cmp_lg_u64 s[24:25], 0
	s_cselect_b32 s32, 47, 49
	v_cndmask_b32_e64 v153, 64, v219, s[30:31]
	v_cndmask_b32_e64 v154, v220, v221, s[20:21]
	s_nop 1
	v_readlane_b32 s26, v255, s32
	s_add_i32 s32, s32, 1
	s_nop 3
	v_readlane_b32 s27, v255, s32
	s_nop 1
	v_mov_b32_e32 v132, s26
	v_mov_b32_e32 v133, s27
	v_or_b32_e32 v0, 0xc0000, v136
	v_cndmask_b32_e64 v136, v136, v0, s[28:29]
	v_cndmask_b32_e64 v0, v154, v222, s[30:31]
	v_cvt_f32_ubyte0_e32 v154, v153
	v_lshlrev_b64 v[134:135], 1, v[134:135]
	v_rcp_iflag_f32_e32 v154, v154
	v_mad_i64_i32 v[134:135], s[26:27], v181, s84, v[134:135]
	v_or_b32_e32 v152, 0x80000, v150
	v_readlane_b32 s26, v255, 14
	v_cndmask_b32_e64 v150, v150, v152, s[28:29]
	v_readlane_b32 s27, v255, 15
	v_sub_u32_e32 v155, 0, v130
	v_sub_u32_e32 v158, 0, v153
	v_lshl_add_u64 v[156:157], v[150:151], 1, s[26:27]
	v_mul_f32_e32 v150, 0x4f7ffffe, v154
	v_cvt_u32_f32_e32 v159, v150
	v_lshlrev_b32_e32 v0, 2, v0
	v_max_i32_e32 v152, v130, v155
	v_lshl_add_u64 v[154:155], s[12:13], 0, v[0:1]
	v_mul_lo_u32 v0, v158, v159
	v_mul_hi_u32 v0, v159, v0
	v_add_u32_e32 v0, v159, v0
	v_lshl_add_u64 v[134:135], v[130:131], 1, v[134:135]
	v_mul_hi_u32 v0, v152, v0
	v_lshl_add_u64 v[150:151], s[14:15], 0, v[134:135]
	v_mul_lo_u32 v134, v0, v153
	v_sub_u32_e32 v134, v152, v134
	v_add_u32_e32 v135, 1, v0
	v_cmp_ge_u32_e32 vcc, v134, v153
	v_mov_b32_e32 v145, v1
	v_lshl_add_u64 v[136:137], v[136:137], 1, s[92:93]
	v_cndmask_b32_e32 v0, v0, v135, vcc
	v_sub_u32_e32 v135, v134, v153
	v_cndmask_b32_e32 v134, v134, v135, vcc
	v_add_u32_e32 v135, 1, v0
	v_cmp_ge_u32_e32 vcc, v134, v153
	s_xor_b64 s[24:25], s[24:25], -1
	v_cndmask_b32_e64 v140, 1, 2, s[30:31]
	v_cndmask_b32_e32 v0, v0, v135, vcc
	v_xor_b32_e32 v0, v0, v131
	v_sub_u32_e32 v152, v0, v131
	v_mul_lo_u32 v0, v152, v153
	v_sub_u32_e32 v130, v130, v0
	v_ashrrev_i32_e32 v131, 31, v130
	v_lshlrev_b64 v[134:135], 1, v[130:131]
	v_lshl_add_u64 v[130:131], v[130:131], 2, v[154:155]
	v_lshl_add_u64 v[158:159], v[130:131], 0, v[144:145]
	v_cndmask_b32_e64 v142, 6, 7, s[30:31]
	v_add3_u32 v141, v166, v180, v182
	v_mov_b32_e32 v139, v1
	v_lshlrev_b32_e32 v162, 5, v181
	v_lshl_add_u64 v[146:147], s[78:79], 0, v[144:145]
	v_lshl_add_u64 v[148:149], s[6:7], 0, v[144:145]
	v_ashrrev_i32_e32 v153, 31, v152
	v_lshl_add_u64 v[154:155], v[136:137], 0, v[134:135]
	v_lshl_add_u64 v[156:157], v[156:157], 0, v[134:135]
	s_mov_b64 s[26:27], 0
	s_waitcnt vmcnt(0)
	v_lshl_add_u64 v[130:131], s[90:91], 2, v[132:133]
	v_lshl_add_u64 v[144:145], v[130:131], 0, v[144:145]
	global_load_dwordx4 v[232:235], v[144:145], off
	global_load_dwordx4 v[236:239], v[144:145], off offset:128
	v_and_b32_e32 v0, 0x7fe0, v162
	v_lshlrev_b32_e32 v0, 2, v0
	v_lshl_add_u64 v[250:251], v[146:147], 0, v[0:1]
	global_load_dwordx4 v[242:245], v[250:251], off
	v_lshl_add_u64 v[250:251], v[148:149], 0, v[0:1]
	global_load_dwordx4 v[246:249], v[250:251], off
	global_load_dword v227, v[250:251], off
	global_load_dword v227, v[250:251], off
	s_branch .LBB0_768
